# W_o / FFN2 residual epilogues batched (loads per column quarter issued together, counted vmcnt) on the all-DMA GEMMs
# speedup vs baseline: 1.0059x; 1.0025x over previous
.LBB0_127:
	v_mov_b32_e32 v67, v169
	s_mov_b32 s11, s8
	v_lshrrev_b32_e32 v69, 4, v67
	v_ashrrev_i32_e32 v71, 3, v67
	v_lshrrev_b32_e32 v77, 1, v67
	v_and_b32_e32 v80, 4, v69
	v_and_b32_e32 v81, 3, v71
	v_and_b32_e32 v73, 7, v67
	v_xor_b32_e32 v75, v71, v67
	v_and_b32_e32 v77, 16, v77
	v_and_b32_e32 v79, 8, v69
	v_or_b32_e32 v82, v80, v81
	v_lshlrev_b32_e32 v75, 4, v75
	v_or3_b32 v77, v77, v79, v82
	v_bitop3_b32 v79, v80, v73, v81 bitop3:0x36
	v_lshlrev_b32_e32 v71, 7, v71
	v_lshlrev_b32_e32 v79, 4, v79
	v_and_or_b32 v122, v75, s24, v71
	v_lshl_or_b32 v121, v77, 7, v79
	v_lshlrev_b32_e32 v34, 7, v67
	v_and_b32_e32 v35, 0x780, v34
	v_and_b32_e32 v123, 0x2780, v34
	v_bitop3_b32 v34, v69, v73, 3 bitop3:0x6c
	v_bfe_u32 v77, v67, 4, 2
	v_lshlrev_b32_e32 v124, 4, v34
	v_lshlrev_b32_e32 v34, 6, v67
	v_mov_b32_e32 v75, v1
	v_and_or_b32 v125, v34, s30, v35
	v_bitop3_b32 v34, v77, v73, 4 bitop3:0x36
	v_mov_b32_e32 v73, v1
	v_mov_b32_e32 v67, v1
	v_mov_b32_e32 v69, v1
	v_mov_b32_e32 v77, v1
	v_mov_b32_e32 v71, v1
	v_mov_b32_e32 v79, v1
	v_lshl_add_u64 v[100:101], v[74:75], 1, s[28:29]
	v_mov_b32_e32 v74, 0
	s_mov_b32 s5, s10
	s_mov_b32 s4, s9
	v_lshlrev_b32_e32 v126, 4, v34
	v_lshl_add_u64 v[98:99], v[72:73], 1, s[28:29]
	v_lshl_add_u64 v[102:103], v[76:77], 1, s[28:29]
	v_lshl_add_u64 v[104:105], v[78:79], 1, s[28:29]
	v_lshlrev_b64 v[106:107], 1, v[0:1]
	v_lshlrev_b64 v[108:109], 1, v[66:67]
	v_lshlrev_b64 v[110:111], 1, v[68:69]
	v_lshlrev_b64 v[112:113], 1, v[70:71]
	s_mov_b32 s8, -2
	s_mov_b64 s[42:43], s[72:73]
	v_mov_b32_e32 v75, v74
	v_mov_b32_e32 v76, v74
	v_mov_b32_e32 v77, v74
	v_mov_b32_e32 v62, v74
	v_mov_b32_e32 v63, v74
	v_mov_b32_e32 v64, v74
	v_mov_b32_e32 v65, v74
	v_mov_b32_e32 v66, v74
	v_mov_b32_e32 v67, v74
	v_mov_b32_e32 v68, v74
	v_mov_b32_e32 v69, v74
	v_mov_b32_e32 v58, v74
	v_mov_b32_e32 v59, v74
	v_mov_b32_e32 v60, v74
	v_mov_b32_e32 v61, v74
	v_mov_b32_e32 v70, v74
	v_mov_b32_e32 v71, v74
	v_mov_b32_e32 v72, v74
	v_mov_b32_e32 v73, v74
	v_mov_b32_e32 v54, v74
	v_mov_b32_e32 v55, v74
	v_mov_b32_e32 v56, v74
	v_mov_b32_e32 v57, v74
	v_mov_b32_e32 v78, v74
	v_mov_b32_e32 v79, v74
	v_mov_b32_e32 v80, v74
	v_mov_b32_e32 v81, v74
	v_mov_b32_e32 v50, v74
	v_mov_b32_e32 v51, v74
	v_mov_b32_e32 v52, v74
	v_mov_b32_e32 v53, v74
	v_mov_b32_e32 v82, v74
	v_mov_b32_e32 v83, v74
	v_mov_b32_e32 v84, v74
	v_mov_b32_e32 v85, v74
	v_mov_b32_e32 v46, v74
	v_mov_b32_e32 v47, v74
	v_mov_b32_e32 v48, v74
	v_mov_b32_e32 v49, v74
	v_mov_b32_e32 v86, v74
	v_mov_b32_e32 v87, v74
	v_mov_b32_e32 v88, v74
	v_mov_b32_e32 v89, v74
	v_mov_b32_e32 v42, v74
	v_mov_b32_e32 v43, v74
	v_mov_b32_e32 v44, v74
	v_mov_b32_e32 v45, v74
	v_mov_b32_e32 v90, v74
	v_mov_b32_e32 v91, v74
	v_mov_b32_e32 v92, v74
	v_mov_b32_e32 v93, v74
	v_mov_b32_e32 v38, v74
	v_mov_b32_e32 v39, v74
	v_mov_b32_e32 v40, v74
	v_mov_b32_e32 v41, v74
	v_mov_b32_e32 v94, v74
	v_mov_b32_e32 v95, v74
	v_mov_b32_e32 v96, v74
	v_mov_b32_e32 v97, v74
	v_mov_b32_e32 v34, v74
	v_mov_b32_e32 v35, v74
	v_mov_b32_e32 v36, v74
	v_mov_b32_e32 v37, v74
	s_waitcnt vmcnt(0)
	s_waitcnt lgkmcnt(0)
	s_barrier
	v_add_u32_e32 v127, v124, v123
	v_add_u32_e32 v129, v124, v125
	v_add_u32_e32 v128, v126, v125
	v_add_u32_e32 v130, v126, v123
	v_lshrrev_b32_e32 v218, 6, v169
	v_lshlrev_b32_e32 v218, 10, v218
	v_lshrrev_b32_e32 v219, 3, v169
	v_readfirstlane_b32 s100, v218
	v_and_b32_e32 v218, 3, v219
	v_bfe_u32 v220, v219, 4, 1
	v_lshl_or_b32 v218, v220, 2, v218
	v_bfe_u32 v220, v219, 2, 1
	v_lshl_or_b32 v218, v220, 3, v218
	v_bfe_u32 v220, v219, 3, 1
	v_lshl_or_b32 v218, v220, 4, v218
	v_sub_u32_e32 v218, v218, v219
	v_mul_i32_i24_e32 v218, 0x1600, v218
	v_and_b32_e32 v219, 7, v219
	v_lshlrev_b32_e32 v219, 4, v219
	v_add_u32_e32 v206, 0x7511000, v106
	v_xor_b32_e32 v194, v206, v219
	v_mov_b32_e32 v207, v98
	v_add_u32_e32 v195, v207, v218
	v_xor_b32_e32 v195, v195, v219
	v_add_u32_e32 v208, 0x7511000, v108
	v_xor_b32_e32 v196, v208, v219
	v_mov_b32_e32 v209, v100
	v_add_u32_e32 v197, v209, v218
	v_xor_b32_e32 v197, v197, v219
	v_add_u32_e32 v214, 0x7511000, v110
	v_xor_b32_e32 v202, v214, v219
	v_mov_b32_e32 v215, v102
	v_add_u32_e32 v203, v215, v218
	v_xor_b32_e32 v203, v203, v219
	v_add_u32_e32 v216, 0x7511000, v112
	v_xor_b32_e32 v204, v216, v219
	v_mov_b32_e32 v217, v104
	v_add_u32_e32 v205, v217, v218
	v_xor_b32_e32 v205, v205, v219
.LBB0_128:
	s_setprio 1
	s_add_u32 s98, s42, s27
	s_addc_u32 s99, s43, 0
	s_add_u32 s98, s98, 0x80
	s_addc_u32 s99, s99, 0
	ds_read_b128 v[132:135], v127 offset:16384
	ds_read_b128 v[140:143], v129
	ds_read_b128 v[152:155], v127 offset:18432
	ds_read_b128 v[160:163], v127 offset:20480
	ds_read_b128 v[164:167], v127 offset:22528
	ds_read_b128 v[144:147], v129 offset:2048
	ds_read_b128 v[148:151], v129 offset:4096
	ds_read_b128 v[156:159], v129 offset:6144
	s_add_u32 m0, s100, 0x8000
	s_waitcnt lgkmcnt(6)
	v_mfma_f32_16x16x32_bf16 v[34:37], v[132:135], v[140:143], v[34:37]
	global_load_lds_dwordx4 v194, s[98:99]
	s_waitcnt lgkmcnt(5)
	v_mfma_f32_16x16x32_bf16 v[94:97], v[152:155], v[140:143], v[94:97]
	ds_read_b128 v[198:201], v128
	s_add_u32 m0, s100, 0xc000
	s_waitcnt lgkmcnt(5)
	v_mfma_f32_16x16x32_bf16 v[38:41], v[160:163], v[140:143], v[38:41]
	global_load_lds_dwordx4 v195, s[98:99]
	s_waitcnt lgkmcnt(4)
	v_mfma_f32_16x16x32_bf16 v[90:93], v[164:167], v[140:143], v[90:93]
	ds_read_b128 v[140:143], v128 offset:2048
	s_add_u32 m0, s100, 0x9000
	s_waitcnt lgkmcnt(4)
	v_mfma_f32_16x16x32_bf16 v[42:45], v[132:135], v[144:147], v[42:45]
	global_load_lds_dwordx4 v196, s[98:99]
	v_mfma_f32_16x16x32_bf16 v[86:89], v[152:155], v[144:147], v[86:89]
	ds_read_b128 v[210:213], v128 offset:4096
	s_add_u32 m0, s100, 0xd000
	v_mfma_f32_16x16x32_bf16 v[46:49], v[160:163], v[144:147], v[46:49]
	global_load_lds_dwordx4 v197, s[98:99]
	v_mfma_f32_16x16x32_bf16 v[82:85], v[164:167], v[144:147], v[82:85]
	ds_read_b128 v[144:147], v128 offset:6144
	s_add_u32 m0, s100, 0xa000
	s_waitcnt lgkmcnt(5)
	v_mfma_f32_16x16x32_bf16 v[50:53], v[132:135], v[148:151], v[50:53]
	global_load_lds_dwordx4 v202, s[98:99]
	v_mfma_f32_16x16x32_bf16 v[78:81], v[152:155], v[148:151], v[78:81]
	ds_read_b128 v[222:225], v130 offset:16384
	s_add_u32 m0, s100, 0xe000
	v_mfma_f32_16x16x32_bf16 v[54:57], v[160:163], v[148:151], v[54:57]
	global_load_lds_dwordx4 v203, s[98:99]
	v_mfma_f32_16x16x32_bf16 v[70:73], v[164:167], v[148:151], v[70:73]
	ds_read_b128 v[148:151], v130 offset:18432
	s_add_u32 m0, s100, 0xb000
	s_waitcnt lgkmcnt(6)
	v_mfma_f32_16x16x32_bf16 v[58:61], v[132:135], v[156:159], v[58:61]
	global_load_lds_dwordx4 v204, s[98:99]
	v_mfma_f32_16x16x32_bf16 v[66:69], v[152:155], v[156:159], v[66:69]
	ds_read_b128 v[152:155], v130 offset:20480
	s_add_u32 m0, s100, 0xf000
	v_mfma_f32_16x16x32_bf16 v[62:65], v[160:163], v[156:159], v[62:65]
	global_load_lds_dwordx4 v205, s[98:99]
	v_mfma_f32_16x16x32_bf16 v[74:77], v[164:167], v[156:159], v[74:77]
	ds_read_b128 v[156:159], v130 offset:22528
	s_waitcnt lgkmcnt(3)
	v_mfma_f32_16x16x32_bf16 v[34:37], v[222:225], v[198:201], v[34:37]
	s_waitcnt lgkmcnt(2)
	v_mfma_f32_16x16x32_bf16 v[94:97], v[148:151], v[198:201], v[94:97]
	s_waitcnt lgkmcnt(1)
	v_mfma_f32_16x16x32_bf16 v[38:41], v[152:155], v[198:201], v[38:41]
	s_waitcnt lgkmcnt(0)
	v_mfma_f32_16x16x32_bf16 v[90:93], v[156:159], v[198:201], v[90:93]
	v_mfma_f32_16x16x32_bf16 v[42:45], v[222:225], v[140:143], v[42:45]
	v_mfma_f32_16x16x32_bf16 v[86:89], v[148:151], v[140:143], v[86:89]
	v_mfma_f32_16x16x32_bf16 v[46:49], v[152:155], v[140:143], v[46:49]
	v_mfma_f32_16x16x32_bf16 v[82:85], v[156:159], v[140:143], v[82:85]
	v_mfma_f32_16x16x32_bf16 v[50:53], v[222:225], v[210:213], v[50:53]
	v_mfma_f32_16x16x32_bf16 v[78:81], v[148:151], v[210:213], v[78:81]
	v_mfma_f32_16x16x32_bf16 v[54:57], v[152:155], v[210:213], v[54:57]
	v_mfma_f32_16x16x32_bf16 v[70:73], v[156:159], v[210:213], v[70:73]
	v_mfma_f32_16x16x32_bf16 v[58:61], v[222:225], v[144:147], v[58:61]
	v_mfma_f32_16x16x32_bf16 v[66:69], v[148:151], v[144:147], v[66:69]
	v_mfma_f32_16x16x32_bf16 v[62:65], v[152:155], v[144:147], v[62:65]
	v_mfma_f32_16x16x32_bf16 v[74:77], v[156:159], v[144:147], v[74:77]
	s_waitcnt vmcnt(0)
	s_setprio 0
	s_waitcnt lgkmcnt(0)
	s_barrier
	s_setprio 1
	s_add_u32 s98, s98, 0x80
	s_addc_u32 s99, s99, 0
	ds_read_b128 v[26:29], v127 offset:49152
	ds_read_b128 v[10:13], v129 offset:32768
	ds_read_b128 v[30:33], v127 offset:51200
	ds_read_b128 v[148:151], v127 offset:53248
	ds_read_b128 v[152:155], v127 offset:55296
	ds_read_b128 v[18:21], v129 offset:34816
	ds_read_b128 v[140:143], v129 offset:36864
	ds_read_b128 v[144:147], v129 offset:38912
	s_add_u32 m0, s100, 0x0
	s_waitcnt lgkmcnt(6)
	v_mfma_f32_16x16x32_bf16 v[34:37], v[26:29], v[10:13], v[34:37]
	global_load_lds_dwordx4 v194, s[98:99]
	s_waitcnt lgkmcnt(5)
	v_mfma_f32_16x16x32_bf16 v[94:97], v[30:33], v[10:13], v[94:97]
	ds_read_b128 v[156:159], v128 offset:32768
	s_add_u32 m0, s100, 0x4000
	s_waitcnt lgkmcnt(5)
	v_mfma_f32_16x16x32_bf16 v[38:41], v[148:151], v[10:13], v[38:41]
	global_load_lds_dwordx4 v195, s[98:99]
	s_waitcnt lgkmcnt(4)
	v_mfma_f32_16x16x32_bf16 v[90:93], v[152:155], v[10:13], v[90:93]
	ds_read_b128 v[164:167], v128 offset:34816
	s_add_u32 m0, s100, 0x1000
	s_waitcnt lgkmcnt(4)
	v_mfma_f32_16x16x32_bf16 v[42:45], v[26:29], v[18:21], v[42:45]
	global_load_lds_dwordx4 v196, s[98:99]
	v_mfma_f32_16x16x32_bf16 v[86:89], v[30:33], v[18:21], v[86:89]
	ds_read_b128 v[198:201], v128 offset:36864
	s_add_u32 m0, s100, 0x5000
	v_mfma_f32_16x16x32_bf16 v[46:49], v[148:151], v[18:21], v[46:49]
	global_load_lds_dwordx4 v197, s[98:99]
	v_mfma_f32_16x16x32_bf16 v[82:85], v[152:155], v[18:21], v[82:85]
	ds_read_b128 v[210:213], v128 offset:38912
	s_add_u32 m0, s100, 0x2000
	s_waitcnt lgkmcnt(5)
	v_mfma_f32_16x16x32_bf16 v[50:53], v[26:29], v[140:143], v[50:53]
	global_load_lds_dwordx4 v202, s[98:99]
	v_mfma_f32_16x16x32_bf16 v[78:81], v[30:33], v[140:143], v[78:81]
	ds_read_b128 v[222:225], v130 offset:49152
	s_add_u32 m0, s100, 0x6000
	v_mfma_f32_16x16x32_bf16 v[54:57], v[148:151], v[140:143], v[54:57]
	global_load_lds_dwordx4 v203, s[98:99]
	v_mfma_f32_16x16x32_bf16 v[70:73], v[152:155], v[140:143], v[70:73]
	ds_read_b128 v[140:143], v130 offset:51200
	s_add_u32 m0, s100, 0x3000
	s_waitcnt lgkmcnt(6)
	v_mfma_f32_16x16x32_bf16 v[58:61], v[26:29], v[144:147], v[58:61]
	global_load_lds_dwordx4 v204, s[98:99]
	v_mfma_f32_16x16x32_bf16 v[66:69], v[30:33], v[144:147], v[66:69]
	ds_read_b128 v[230:233], v130 offset:53248
	s_add_u32 m0, s100, 0x7000
	v_mfma_f32_16x16x32_bf16 v[62:65], v[148:151], v[144:147], v[62:65]
	global_load_lds_dwordx4 v205, s[98:99]
	v_mfma_f32_16x16x32_bf16 v[74:77], v[152:155], v[144:147], v[74:77]
	ds_read_b128 v[144:147], v130 offset:55296
	s_waitcnt lgkmcnt(3)
	v_mfma_f32_16x16x32_bf16 v[34:37], v[222:225], v[156:159], v[34:37]
	s_waitcnt lgkmcnt(2)
	v_mfma_f32_16x16x32_bf16 v[94:97], v[140:143], v[156:159], v[94:97]
	s_waitcnt lgkmcnt(1)
	v_mfma_f32_16x16x32_bf16 v[38:41], v[230:233], v[156:159], v[38:41]
	s_waitcnt lgkmcnt(0)
	v_mfma_f32_16x16x32_bf16 v[90:93], v[144:147], v[156:159], v[90:93]
	v_mfma_f32_16x16x32_bf16 v[42:45], v[222:225], v[164:167], v[42:45]
	v_mfma_f32_16x16x32_bf16 v[86:89], v[140:143], v[164:167], v[86:89]
	v_mfma_f32_16x16x32_bf16 v[46:49], v[230:233], v[164:167], v[46:49]
	v_mfma_f32_16x16x32_bf16 v[82:85], v[144:147], v[164:167], v[82:85]
	v_mfma_f32_16x16x32_bf16 v[50:53], v[222:225], v[198:201], v[50:53]
	v_mfma_f32_16x16x32_bf16 v[78:81], v[140:143], v[198:201], v[78:81]
	v_mfma_f32_16x16x32_bf16 v[54:57], v[230:233], v[198:201], v[54:57]
	v_mfma_f32_16x16x32_bf16 v[70:73], v[144:147], v[198:201], v[70:73]
	v_mfma_f32_16x16x32_bf16 v[58:61], v[222:225], v[210:213], v[58:61]
	v_mfma_f32_16x16x32_bf16 v[66:69], v[140:143], v[210:213], v[66:69]
	v_mfma_f32_16x16x32_bf16 v[62:65], v[230:233], v[210:213], v[62:65]
	v_mfma_f32_16x16x32_bf16 v[74:77], v[144:147], v[210:213], v[74:77]
	s_waitcnt vmcnt(0)
	s_setprio 0
	s_add_i32 s8, s8, 2
	s_add_u32 s42, s42, 0x100
	s_addc_u32 s43, s43, 0
	s_cmp_lt_u32 s8, 40
	s_waitcnt lgkmcnt(0)
	s_barrier
	s_cbranch_scc1 .LBB0_128
	v_mov_b32_e32 v2, v194
	v_mov_b32_e32 v3, v195
	v_mov_b32_e32 v4, v196
	v_mov_b32_e32 v5, v197
	v_mov_b32_e32 v6, v202
	v_mov_b32_e32 v7, v203
	v_mov_b32_e32 v8, v204
	v_mov_b32_e32 v9, v205
	s_add_u32 s98, s42, s27
	s_addc_u32 s99, s43, 0
	s_add_u32 s98, s98, 0x80
	s_addc_u32 s99, s99, 0
	s_add_i32 s8, s11, s2
	s_cmpk_lt_u32 s8, 0x100
	s_cselect_b32 s10, s8, s11
	s_lshr_b32 s9, s10, 3
	s_and_b32 s9, s9, 0x1fffff8
	s_add_i32 s9, s9, s21
	s_and_b32 s11, s10, 7
	s_or_b32 s9, s9, s11
	v_mov_b32_e32 v0, v169
	s_lshl_b32 s9, s9, 7
	s_movk_i32 s11, 0xb00
	v_lshrrev_b32_e32 v98, 3, v0
	v_add_u32_e32 v98, s9, v98
	v_lshlrev_b32_e32 v0, 3, v0
	v_mul_lo_u32 v98, v98, s11
	s_lshl_b32 s10, s10, 4
	v_and_or_b32 v0, v0, 56, v98
	v_mov_b32_e32 v98, v169
	s_and_b32 s10, s10, 0x380
	s_cmpk_gt_u32 s8, 0xff
	s_cselect_b32 s101, 1, 0
	v_lshrrev_b32_e32 v99, 3, v98
	v_add_u32_e32 v99, s10, v99
	v_lshlrev_b32_e32 v98, 3, v98
	v_mul_lo_u32 v99, v99, s11
	v_and_or_b32 v164, v98, 56, v99
	v_add_u32_e32 v114, 0x16000, v0
	v_add_u32_e32 v124, 0x2c000, v0
	v_add_u32_e32 v136, 0x42000, v0
	v_add_u32_e32 v174, 0x16000, v164
	v_add_u32_e32 v176, 0x2c000, v164
	v_add_u32_e32 v178, 0x42000, v164
	s_setprio 1
	ds_read_b128 v[98:101], v127 offset:16384
	ds_read_b128 v[102:105], v129
	ds_read_b128 v[110:113], v127 offset:18432
	ds_read_b128 v[144:147], v127 offset:20480
	ds_read_b128 v[148:151], v127 offset:22528
	ds_read_b128 v[106:109], v129 offset:2048
	ds_read_b128 v[132:135], v129 offset:4096
	ds_read_b128 v[140:143], v129 offset:6144
	v_lshrrev_b32_e32 v14, 3, v169
	v_and_b32_e32 v15, 3, v14
	v_bfe_u32 v16, v14, 4, 1
	v_lshl_or_b32 v15, v16, 2, v15
	v_bfe_u32 v16, v14, 2, 1
	v_lshl_or_b32 v15, v16, 3, v15
	v_bfe_u32 v16, v14, 3, 1
	v_lshl_or_b32 v15, v16, 4, v15
	v_sub_u32_e32 v15, v15, v14
	v_mul_i32_i24_e32 v15, 0xb00, v15
	v_and_b32_e32 v14, 7, v14
	v_lshlrev_b32_e32 v14, 3, v14
	v_xor_b32_e32 v0, v0, v14
	v_add_u32_e32 v164, v164, v15
	v_xor_b32_e32 v164, v164, v14
	v_xor_b32_e32 v114, v114, v14
	v_add_u32_e32 v174, v174, v15
	v_xor_b32_e32 v174, v174, v14
	v_xor_b32_e32 v124, v124, v14
	v_add_u32_e32 v176, v176, v15
	v_xor_b32_e32 v176, v176, v14
	v_xor_b32_e32 v136, v136, v14
	v_add_u32_e32 v178, v178, v15
	v_xor_b32_e32 v178, v178, v14
	v_readlane_b32 s14, v254, 33
	v_readlane_b32 s15, v254, 34
	v_mov_b32_e32 v165, v1
	v_mov_b32_e32 v115, v1
	v_mov_b32_e32 v175, v1
	v_mov_b32_e32 v125, v1
	v_mov_b32_e32 v177, v1
	v_mov_b32_e32 v137, v1
	v_mov_b32_e32 v179, v1
	v_lshl_add_u64 v[180:181], v[0:1], 1, s[14:15]
	v_lshl_add_u64 v[186:187], v[164:165], 1, s[38:39]
	v_lshl_add_u64 v[114:115], v[114:115], 1, s[14:15]
	v_lshl_add_u64 v[174:175], v[174:175], 1, s[38:39]
	v_lshl_add_u64 v[188:189], v[124:125], 1, s[14:15]
	v_lshl_add_u64 v[176:177], v[176:177], 1, s[38:39]
	v_lshl_add_u64 v[136:137], v[136:137], 1, s[14:15]
	v_lshl_add_u64 v[178:179], v[178:179], 1, s[38:39]
	s_add_u32 m0, s100, 0x8000
	s_waitcnt lgkmcnt(6)
	v_mfma_f32_16x16x32_bf16 v[152:155], v[98:101], v[102:105], v[34:37]
	global_load_lds_dwordx4 v2, s[98:99]
	s_waitcnt lgkmcnt(5)
	v_mfma_f32_16x16x32_bf16 v[94:97], v[110:113], v[102:105], v[94:97]
	ds_read_b128 v[156:159], v128
	s_add_u32 m0, s100, 0xc000
	s_waitcnt lgkmcnt(5)
	v_mfma_f32_16x16x32_bf16 v[160:163], v[144:147], v[102:105], v[38:41]
	global_load_lds_dwordx4 v3, s[98:99]
	s_waitcnt lgkmcnt(4)
	v_mfma_f32_16x16x32_bf16 v[90:93], v[148:151], v[102:105], v[90:93]
	ds_read_b128 v[102:105], v128 offset:2048
	s_add_u32 m0, s100, 0x9000
	s_waitcnt lgkmcnt(4)
	v_mfma_f32_16x16x32_bf16 v[164:167], v[98:101], v[106:109], v[42:45]
	global_load_lds_dwordx4 v4, s[98:99]
	v_mfma_f32_16x16x32_bf16 v[86:89], v[110:113], v[106:109], v[86:89]
	ds_read_b128 v[194:197], v128 offset:4096
	s_add_u32 m0, s100, 0xd000
	v_mfma_f32_16x16x32_bf16 v[198:201], v[144:147], v[106:109], v[46:49]
	global_load_lds_dwordx4 v5, s[98:99]
	v_mfma_f32_16x16x32_bf16 v[82:85], v[148:151], v[106:109], v[82:85]
	ds_read_b128 v[106:109], v128 offset:6144
	s_add_u32 m0, s100, 0xa000
	s_waitcnt lgkmcnt(5)
	v_mfma_f32_16x16x32_bf16 v[202:205], v[98:101], v[132:135], v[50:53]
	global_load_lds_dwordx4 v6, s[98:99]
	v_mfma_f32_16x16x32_bf16 v[78:81], v[110:113], v[132:135], v[78:81]
	ds_read_b128 v[206:209], v130 offset:16384
	s_add_u32 m0, s100, 0xe000
	v_mfma_f32_16x16x32_bf16 v[210:213], v[144:147], v[132:135], v[54:57]
	global_load_lds_dwordx4 v7, s[98:99]
	v_mfma_f32_16x16x32_bf16 v[70:73], v[148:151], v[132:135], v[70:73]
	ds_read_b128 v[132:135], v130 offset:18432
	s_add_u32 m0, s100, 0xb000
	s_waitcnt lgkmcnt(6)
	v_mfma_f32_16x16x32_bf16 v[98:101], v[98:101], v[140:143], v[58:61]
	global_load_lds_dwordx4 v8, s[98:99]
	v_mfma_f32_16x16x32_bf16 v[66:69], v[110:113], v[140:143], v[66:69]
	ds_read_b128 v[110:113], v130 offset:20480
	s_add_u32 m0, s100, 0xf000
	v_mfma_f32_16x16x32_bf16 v[144:147], v[144:147], v[140:143], v[62:65]
	global_load_lds_dwordx4 v9, s[98:99]
	v_mfma_f32_16x16x32_bf16 v[74:77], v[148:151], v[140:143], v[74:77]
	ds_read_b128 v[140:143], v130 offset:22528
	s_waitcnt lgkmcnt(3)
	v_mfma_f32_16x16x32_bf16 v[148:151], v[206:209], v[156:159], v[152:155]
	s_waitcnt lgkmcnt(2)
	v_mfma_f32_16x16x32_bf16 v[94:97], v[132:135], v[156:159], v[94:97]
	s_waitcnt lgkmcnt(1)
	v_mfma_f32_16x16x32_bf16 v[152:155], v[110:113], v[156:159], v[160:163]
	s_waitcnt lgkmcnt(0)
	v_mfma_f32_16x16x32_bf16 v[90:93], v[140:143], v[156:159], v[90:93]
	v_mfma_f32_16x16x32_bf16 v[156:159], v[206:209], v[102:105], v[164:167]
	v_mfma_f32_16x16x32_bf16 v[86:89], v[132:135], v[102:105], v[86:89]
	v_mfma_f32_16x16x32_bf16 v[160:163], v[110:113], v[102:105], v[198:201]
	v_mfma_f32_16x16x32_bf16 v[82:85], v[140:143], v[102:105], v[82:85]
	v_mfma_f32_16x16x32_bf16 v[102:105], v[206:209], v[194:197], v[202:205]
	v_mfma_f32_16x16x32_bf16 v[78:81], v[132:135], v[194:197], v[78:81]
	v_mfma_f32_16x16x32_bf16 v[164:167], v[110:113], v[194:197], v[210:213]
	v_mfma_f32_16x16x32_bf16 v[70:73], v[140:143], v[194:197], v[70:73]
	v_mfma_f32_16x16x32_bf16 v[98:101], v[206:209], v[106:109], v[98:101]
	v_mfma_f32_16x16x32_bf16 v[66:69], v[132:135], v[106:109], v[66:69]
	v_mfma_f32_16x16x32_bf16 v[110:113], v[110:113], v[106:109], v[144:147]
	v_mfma_f32_16x16x32_bf16 v[74:77], v[140:143], v[106:109], v[74:77]
	s_waitcnt vmcnt(0)
	s_setprio 0
	s_waitcnt lgkmcnt(0)
	s_barrier
	s_setprio 1
	ds_read_b128 v[26:29], v127 offset:49152
	ds_read_b128 v[10:13], v129 offset:32768
	ds_read_b128 v[30:33], v127 offset:51200
	ds_read_b128 v[132:135], v127 offset:53248
	ds_read_b128 v[140:143], v127 offset:55296
	ds_read_b128 v[18:21], v129 offset:34816
	ds_read_b128 v[106:109], v129 offset:36864
	ds_read_b128 v[122:125], v129 offset:38912
	s_add_u32 m0, s100, 0x0
	s_waitcnt lgkmcnt(6)
	v_mfma_f32_16x16x32_bf16 v[144:147], v[26:29], v[10:13], v[148:151]
	global_load_lds_dwordx4 v[180:181], off
	s_waitcnt lgkmcnt(5)
	v_mfma_f32_16x16x32_bf16 v[94:97], v[30:33], v[10:13], v[94:97]
	ds_read_b128 v[148:151], v128 offset:32768
	s_add_u32 m0, s100, 0x4000
	s_waitcnt lgkmcnt(5)
	v_mfma_f32_16x16x32_bf16 v[152:155], v[132:135], v[10:13], v[152:155]
	global_load_lds_dwordx4 v[186:187], off
	s_waitcnt lgkmcnt(4)
	v_mfma_f32_16x16x32_bf16 v[90:93], v[140:143], v[10:13], v[90:93]
	ds_read_b128 v[194:197], v128 offset:34816
	s_add_u32 m0, s100, 0x1000
	s_waitcnt lgkmcnt(4)
	v_mfma_f32_16x16x32_bf16 v[156:159], v[26:29], v[18:21], v[156:159]
	global_load_lds_dwordx4 v[114:115], off
	v_mfma_f32_16x16x32_bf16 v[86:89], v[30:33], v[18:21], v[86:89]
	ds_read_b128 v[198:201], v128 offset:36864
	s_add_u32 m0, s100, 0x5000
	v_mfma_f32_16x16x32_bf16 v[160:163], v[132:135], v[18:21], v[160:163]
	global_load_lds_dwordx4 v[174:175], off
	v_mfma_f32_16x16x32_bf16 v[82:85], v[140:143], v[18:21], v[82:85]
	ds_read_b128 v[126:129], v128 offset:38912
	s_add_u32 m0, s100, 0x2000
	s_waitcnt lgkmcnt(5)
	v_mfma_f32_16x16x32_bf16 v[202:205], v[26:29], v[106:109], v[102:105]
	global_load_lds_dwordx4 v[188:189], off
	v_mfma_f32_16x16x32_bf16 v[78:81], v[30:33], v[106:109], v[78:81]
	ds_read_b128 v[206:209], v130 offset:49152
	s_add_u32 m0, s100, 0x6000
	v_mfma_f32_16x16x32_bf16 v[164:167], v[132:135], v[106:109], v[164:167]
	global_load_lds_dwordx4 v[176:177], off
	v_mfma_f32_16x16x32_bf16 v[70:73], v[140:143], v[106:109], v[70:73]
	ds_read_b128 v[210:213], v130 offset:51200
	s_add_u32 m0, s100, 0x3000
	s_waitcnt lgkmcnt(6)
	v_mfma_f32_16x16x32_bf16 v[214:217], v[26:29], v[122:125], v[98:101]
	global_load_lds_dwordx4 v[136:137], off
	v_mfma_f32_16x16x32_bf16 v[66:69], v[30:33], v[122:125], v[66:69]
	ds_read_b128 v[218:221], v130 offset:53248
	s_add_u32 m0, s100, 0x7000
	v_mfma_f32_16x16x32_bf16 v[110:113], v[132:135], v[122:125], v[110:113]
	global_load_lds_dwordx4 v[178:179], off
	v_mfma_f32_16x16x32_bf16 v[122:125], v[140:143], v[122:125], v[74:77]
	s_waitcnt lgkmcnt(2)
	v_mfma_f32_16x16x32_bf16 v[132:135], v[206:209], v[148:151], v[144:147]
	s_waitcnt lgkmcnt(0)
	v_mfma_f32_16x16x32_bf16 v[144:147], v[218:221], v[148:151], v[152:155]
	ds_read_b128 v[152:155], v130 offset:55296
	v_mfma_f32_16x16x32_bf16 v[140:143], v[210:213], v[148:151], v[94:97]
	s_waitcnt lgkmcnt(0)
	v_mfma_f32_16x16x32_bf16 v[148:151], v[152:155], v[148:151], v[90:93]
	v_mfma_f32_16x16x32_bf16 v[98:101], v[152:155], v[194:197], v[82:85]
	v_mfma_f32_16x16x32_bf16 v[90:93], v[210:213], v[198:201], v[78:81]
	v_mfma_f32_16x16x32_bf16 v[82:85], v[152:155], v[198:201], v[70:73]
	v_mfma_f32_16x16x32_bf16 v[78:81], v[206:209], v[126:129], v[214:217]
	v_mfma_f32_16x16x32_bf16 v[74:77], v[210:213], v[126:129], v[66:69]
	v_mfma_f32_16x16x32_bf16 v[66:69], v[218:221], v[126:129], v[110:113]
	v_mfma_f32_16x16x32_bf16 v[70:73], v[152:155], v[126:129], v[122:125]
	v_mfma_f32_16x16x32_bf16 v[156:159], v[206:209], v[194:197], v[156:159]
	v_mfma_f32_16x16x32_bf16 v[106:109], v[210:213], v[194:197], v[86:89]
	v_mfma_f32_16x16x32_bf16 v[102:105], v[218:221], v[194:197], v[160:163]
	v_mfma_f32_16x16x32_bf16 v[94:97], v[206:209], v[198:201], v[202:205]
	v_mfma_f32_16x16x32_bf16 v[86:89], v[218:221], v[198:201], v[164:167]
	s_setprio 0
	v_add_u32_e32 v110, s4, v116
	v_ashrrev_i32_e32 v111, 31, v110
	v_readlane_b32 s44, v253, 18
	v_lshlrev_b64 v[112:113], 12, v[110:111]
	v_or_b32_e32 v0, s5, v117
	v_readlane_b32 s58, v253, 32
	v_readlane_b32 s59, v253, 33
	v_lshlrev_b64 v[114:115], 2, v[0:1]
	v_lshl_add_u64 v[166:167], v[110:111], 3, s[0:1]
	v_lshl_add_u64 v[112:113], s[58:59], 0, v[112:113]
	v_lshl_add_u64 v[164:165], v[112:113], 0, v[114:115]
	s_barrier
	v_readlane_b32 s44, v253, 18
	v_readlane_b32 s45, v253, 19
	v_readlane_b32 s46, v253, 20
	v_readlane_b32 s47, v253, 21
	v_readlane_b32 s48, v253, 22
	v_readlane_b32 s49, v253, 23
	v_readlane_b32 s50, v253, 24
	v_readlane_b32 s51, v253, 25
	v_readlane_b32 s52, v253, 26
	v_readlane_b32 s53, v253, 27
	v_readlane_b32 s54, v253, 28
	v_readlane_b32 s55, v253, 29
	v_readlane_b32 s56, v253, 30
	v_readlane_b32 s57, v253, 31
	v_readlane_b32 s58, v253, 32
	v_readlane_b32 s59, v253, 33
	s_mov_b64 s[42:43], -1
	v_or_b32_e32 v0, s5, v117
	v_lshlrev_b32_e32 v0, 2, v0
	v_add_u32_e32 v110, s4, v116
	v_lshlrev_b32_e32 v160, 3, v110
	v_lshlrev_b32_e32 v110, 12, v110
	v_add_u32_e32 v110, v110, v0
	v_add_u32_e32 v111, s4, v118
	v_lshlrev_b32_e32 v222, 3, v111
	v_lshlrev_b32_e32 v111, 12, v111
	v_add_u32_e32 v111, v111, v0
	v_add_u32_e32 v112, s4, v119
	v_lshlrev_b32_e32 v226, 3, v112
	v_lshlrev_b32_e32 v112, 12, v112
	v_add_u32_e32 v112, v112, v0
	v_add_u32_e32 v113, s4, v120
	v_lshlrev_b32_e32 v230, 3, v113
	v_lshlrev_b32_e32 v113, 12, v113
	v_add_u32_e32 v113, v113, v0
	s_mov_b32 s14, 0x3fb504f3
	global_load_dwordx2 v[114:115], v160, s[0:1]
	global_load_dwordx2 v[122:123], v222, s[0:1]
	global_load_dwordx2 v[124:125], v226, s[0:1]
	global_load_dwordx2 v[126:127], v230, s[0:1]
	global_load_dwordx4 v[128:131], v0, s[34:35]
	global_load_dwordx4 v[152:155], v0, s[40:41]
	global_load_dwordx4 v[160:163], v110, s[58:59]
	global_load_dwordx4 v[222:225], v111, s[58:59]
	global_load_dwordx4 v[226:229], v112, s[58:59]
	global_load_dwordx4 v[230:233], v113, s[58:59]
	s_waitcnt vmcnt(3)
	v_pk_add_f32 v[160:161], v[160:161], v[114:115] op_sel_hi:[1,0] neg_lo:[0,1] neg_hi:[0,1]
	v_pk_add_f32 v[162:163], v[162:163], v[114:115] op_sel_hi:[1,0] neg_lo:[0,1] neg_hi:[0,1]
	v_pk_mul_f32 v[160:161], v[160:161], v[114:115] op_sel:[0,1]
	v_pk_mul_f32 v[162:163], v[162:163], v[114:115] op_sel:[0,1]
	v_pk_fma_f32 v[160:161], v[160:161], v[128:129], v[152:153]
	v_pk_fma_f32 v[162:163], v[162:163], v[130:131], v[154:155]
	v_pk_fma_f32 v[132:133], v[160:161], s[14:15], v[132:133] op_sel_hi:[1,0,1]
	v_pk_fma_f32 v[134:135], v[162:163], s[14:15], v[134:135] op_sel_hi:[1,0,1]
	global_store_dwordx4 v110, v[132:135], s[58:59]
	s_waitcnt vmcnt(3)
	v_pk_add_f32 v[222:223], v[222:223], v[122:123] op_sel_hi:[1,0] neg_lo:[0,1] neg_hi:[0,1]
	v_pk_add_f32 v[224:225], v[224:225], v[122:123] op_sel_hi:[1,0] neg_lo:[0,1] neg_hi:[0,1]
	v_pk_mul_f32 v[222:223], v[222:223], v[122:123] op_sel:[0,1]
	v_pk_mul_f32 v[224:225], v[224:225], v[122:123] op_sel:[0,1]
	v_pk_fma_f32 v[222:223], v[222:223], v[128:129], v[152:153]
	v_pk_fma_f32 v[224:225], v[224:225], v[130:131], v[154:155]
	v_pk_fma_f32 v[156:157], v[222:223], s[14:15], v[156:157] op_sel_hi:[1,0,1]
	v_pk_fma_f32 v[158:159], v[224:225], s[14:15], v[158:159] op_sel_hi:[1,0,1]
	global_store_dwordx4 v111, v[156:159], s[58:59]
	s_waitcnt vmcnt(3)
	v_pk_add_f32 v[226:227], v[226:227], v[124:125] op_sel_hi:[1,0] neg_lo:[0,1] neg_hi:[0,1]
	v_pk_add_f32 v[228:229], v[228:229], v[124:125] op_sel_hi:[1,0] neg_lo:[0,1] neg_hi:[0,1]
	v_pk_mul_f32 v[226:227], v[226:227], v[124:125] op_sel:[0,1]
	v_pk_mul_f32 v[228:229], v[228:229], v[124:125] op_sel:[0,1]
	v_pk_fma_f32 v[226:227], v[226:227], v[128:129], v[152:153]
	v_pk_fma_f32 v[228:229], v[228:229], v[130:131], v[154:155]
	v_pk_fma_f32 v[94:95], v[226:227], s[14:15], v[94:95] op_sel_hi:[1,0,1]
	v_pk_fma_f32 v[96:97], v[228:229], s[14:15], v[96:97] op_sel_hi:[1,0,1]
	global_store_dwordx4 v112, v[94:97], s[58:59]
	s_waitcnt vmcnt(3)
	v_pk_add_f32 v[230:231], v[230:231], v[126:127] op_sel_hi:[1,0] neg_lo:[0,1] neg_hi:[0,1]
	v_pk_add_f32 v[232:233], v[232:233], v[126:127] op_sel_hi:[1,0] neg_lo:[0,1] neg_hi:[0,1]
	v_pk_mul_f32 v[230:231], v[230:231], v[126:127] op_sel:[0,1]
	v_pk_mul_f32 v[232:233], v[232:233], v[126:127] op_sel:[0,1]
	v_pk_fma_f32 v[230:231], v[230:231], v[128:129], v[152:153]
	v_pk_fma_f32 v[232:233], v[232:233], v[130:131], v[154:155]
	v_pk_fma_f32 v[78:79], v[230:231], s[14:15], v[78:79] op_sel_hi:[1,0,1]
	v_pk_fma_f32 v[80:81], v[232:233], s[14:15], v[80:81] op_sel_hi:[1,0,1]
	global_store_dwordx4 v113, v[78:81], s[58:59]
	global_load_dwordx4 v[128:131], v0, s[34:35] offset:16
	global_load_dwordx4 v[152:155], v0, s[40:41] offset:16
	global_load_dwordx4 v[160:163], v110, s[58:59] offset:16
	global_load_dwordx4 v[222:225], v111, s[58:59] offset:16
	global_load_dwordx4 v[226:229], v112, s[58:59] offset:16
	global_load_dwordx4 v[230:233], v113, s[58:59] offset:16
	s_waitcnt vmcnt(3)
	v_pk_add_f32 v[160:161], v[160:161], v[114:115] op_sel_hi:[1,0] neg_lo:[0,1] neg_hi:[0,1]
	v_pk_add_f32 v[162:163], v[162:163], v[114:115] op_sel_hi:[1,0] neg_lo:[0,1] neg_hi:[0,1]
	v_pk_mul_f32 v[160:161], v[160:161], v[114:115] op_sel:[0,1]
	v_pk_mul_f32 v[162:163], v[162:163], v[114:115] op_sel:[0,1]
	v_pk_fma_f32 v[160:161], v[160:161], v[128:129], v[152:153]
	v_pk_fma_f32 v[162:163], v[162:163], v[130:131], v[154:155]
	v_pk_fma_f32 v[140:141], v[160:161], s[14:15], v[140:141] op_sel_hi:[1,0,1]
	v_pk_fma_f32 v[142:143], v[162:163], s[14:15], v[142:143] op_sel_hi:[1,0,1]
	global_store_dwordx4 v110, v[140:143], s[58:59] offset:16
	s_waitcnt vmcnt(3)
	v_pk_add_f32 v[222:223], v[222:223], v[122:123] op_sel_hi:[1,0] neg_lo:[0,1] neg_hi:[0,1]
	v_pk_add_f32 v[224:225], v[224:225], v[122:123] op_sel_hi:[1,0] neg_lo:[0,1] neg_hi:[0,1]
	v_pk_mul_f32 v[222:223], v[222:223], v[122:123] op_sel:[0,1]
	v_pk_mul_f32 v[224:225], v[224:225], v[122:123] op_sel:[0,1]
	v_pk_fma_f32 v[222:223], v[222:223], v[128:129], v[152:153]
	v_pk_fma_f32 v[224:225], v[224:225], v[130:131], v[154:155]
	v_pk_fma_f32 v[106:107], v[222:223], s[14:15], v[106:107] op_sel_hi:[1,0,1]
	v_pk_fma_f32 v[108:109], v[224:225], s[14:15], v[108:109] op_sel_hi:[1,0,1]
	global_store_dwordx4 v111, v[106:109], s[58:59] offset:16
	s_waitcnt vmcnt(3)
	v_pk_add_f32 v[226:227], v[226:227], v[124:125] op_sel_hi:[1,0] neg_lo:[0,1] neg_hi:[0,1]
	v_pk_add_f32 v[228:229], v[228:229], v[124:125] op_sel_hi:[1,0] neg_lo:[0,1] neg_hi:[0,1]
	v_pk_mul_f32 v[226:227], v[226:227], v[124:125] op_sel:[0,1]
	v_pk_mul_f32 v[228:229], v[228:229], v[124:125] op_sel:[0,1]
	v_pk_fma_f32 v[226:227], v[226:227], v[128:129], v[152:153]
	v_pk_fma_f32 v[228:229], v[228:229], v[130:131], v[154:155]
	v_pk_fma_f32 v[90:91], v[226:227], s[14:15], v[90:91] op_sel_hi:[1,0,1]
	v_pk_fma_f32 v[92:93], v[228:229], s[14:15], v[92:93] op_sel_hi:[1,0,1]
	global_store_dwordx4 v112, v[90:93], s[58:59] offset:16
	s_waitcnt vmcnt(3)
	v_pk_add_f32 v[230:231], v[230:231], v[126:127] op_sel_hi:[1,0] neg_lo:[0,1] neg_hi:[0,1]
	v_pk_add_f32 v[232:233], v[232:233], v[126:127] op_sel_hi:[1,0] neg_lo:[0,1] neg_hi:[0,1]
	v_pk_mul_f32 v[230:231], v[230:231], v[126:127] op_sel:[0,1]
	v_pk_mul_f32 v[232:233], v[232:233], v[126:127] op_sel:[0,1]
	v_pk_fma_f32 v[230:231], v[230:231], v[128:129], v[152:153]
	v_pk_fma_f32 v[232:233], v[232:233], v[130:131], v[154:155]
	v_pk_fma_f32 v[74:75], v[230:231], s[14:15], v[74:75] op_sel_hi:[1,0,1]
	v_pk_fma_f32 v[76:77], v[232:233], s[14:15], v[76:77] op_sel_hi:[1,0,1]
	global_store_dwordx4 v113, v[74:77], s[58:59] offset:16
	global_load_dwordx4 v[128:131], v0, s[34:35] offset:128
	global_load_dwordx4 v[152:155], v0, s[40:41] offset:128
	global_load_dwordx4 v[160:163], v110, s[58:59] offset:128
	global_load_dwordx4 v[222:225], v111, s[58:59] offset:128
	global_load_dwordx4 v[226:229], v112, s[58:59] offset:128
	global_load_dwordx4 v[230:233], v113, s[58:59] offset:128
	s_waitcnt vmcnt(3)
	v_pk_add_f32 v[160:161], v[160:161], v[114:115] op_sel_hi:[1,0] neg_lo:[0,1] neg_hi:[0,1]
	v_pk_add_f32 v[162:163], v[162:163], v[114:115] op_sel_hi:[1,0] neg_lo:[0,1] neg_hi:[0,1]
	v_pk_mul_f32 v[160:161], v[160:161], v[114:115] op_sel:[0,1]
	v_pk_mul_f32 v[162:163], v[162:163], v[114:115] op_sel:[0,1]
	v_pk_fma_f32 v[160:161], v[160:161], v[128:129], v[152:153]
	v_pk_fma_f32 v[162:163], v[162:163], v[130:131], v[154:155]
	v_pk_fma_f32 v[144:145], v[160:161], s[14:15], v[144:145] op_sel_hi:[1,0,1]
	v_pk_fma_f32 v[146:147], v[162:163], s[14:15], v[146:147] op_sel_hi:[1,0,1]
	global_store_dwordx4 v110, v[144:147], s[58:59] offset:128
	s_waitcnt vmcnt(3)
	v_pk_add_f32 v[222:223], v[222:223], v[122:123] op_sel_hi:[1,0] neg_lo:[0,1] neg_hi:[0,1]
	v_pk_add_f32 v[224:225], v[224:225], v[122:123] op_sel_hi:[1,0] neg_lo:[0,1] neg_hi:[0,1]
	v_pk_mul_f32 v[222:223], v[222:223], v[122:123] op_sel:[0,1]
	v_pk_mul_f32 v[224:225], v[224:225], v[122:123] op_sel:[0,1]
	v_pk_fma_f32 v[222:223], v[222:223], v[128:129], v[152:153]
	v_pk_fma_f32 v[224:225], v[224:225], v[130:131], v[154:155]
	v_pk_fma_f32 v[102:103], v[222:223], s[14:15], v[102:103] op_sel_hi:[1,0,1]
	v_pk_fma_f32 v[104:105], v[224:225], s[14:15], v[104:105] op_sel_hi:[1,0,1]
	global_store_dwordx4 v111, v[102:105], s[58:59] offset:128
	s_waitcnt vmcnt(3)
	v_pk_add_f32 v[226:227], v[226:227], v[124:125] op_sel_hi:[1,0] neg_lo:[0,1] neg_hi:[0,1]
	v_pk_add_f32 v[228:229], v[228:229], v[124:125] op_sel_hi:[1,0] neg_lo:[0,1] neg_hi:[0,1]
	v_pk_mul_f32 v[226:227], v[226:227], v[124:125] op_sel:[0,1]
	v_pk_mul_f32 v[228:229], v[228:229], v[124:125] op_sel:[0,1]
	v_pk_fma_f32 v[226:227], v[226:227], v[128:129], v[152:153]
	v_pk_fma_f32 v[228:229], v[228:229], v[130:131], v[154:155]
	v_pk_fma_f32 v[86:87], v[226:227], s[14:15], v[86:87] op_sel_hi:[1,0,1]
	v_pk_fma_f32 v[88:89], v[228:229], s[14:15], v[88:89] op_sel_hi:[1,0,1]
	global_store_dwordx4 v112, v[86:89], s[58:59] offset:128
	s_waitcnt vmcnt(3)
	v_pk_add_f32 v[230:231], v[230:231], v[126:127] op_sel_hi:[1,0] neg_lo:[0,1] neg_hi:[0,1]
	v_pk_add_f32 v[232:233], v[232:233], v[126:127] op_sel_hi:[1,0] neg_lo:[0,1] neg_hi:[0,1]
	v_pk_mul_f32 v[230:231], v[230:231], v[126:127] op_sel:[0,1]
	v_pk_mul_f32 v[232:233], v[232:233], v[126:127] op_sel:[0,1]
	v_pk_fma_f32 v[230:231], v[230:231], v[128:129], v[152:153]
	v_pk_fma_f32 v[232:233], v[232:233], v[130:131], v[154:155]
	v_pk_fma_f32 v[66:67], v[230:231], s[14:15], v[66:67] op_sel_hi:[1,0,1]
	v_pk_fma_f32 v[68:69], v[232:233], s[14:15], v[68:69] op_sel_hi:[1,0,1]
	global_store_dwordx4 v113, v[66:69], s[58:59] offset:128
	global_load_dwordx4 v[128:131], v0, s[34:35] offset:144
	global_load_dwordx4 v[152:155], v0, s[40:41] offset:144
	global_load_dwordx4 v[160:163], v110, s[58:59] offset:144
	global_load_dwordx4 v[222:225], v111, s[58:59] offset:144
	global_load_dwordx4 v[226:229], v112, s[58:59] offset:144
	global_load_dwordx4 v[230:233], v113, s[58:59] offset:144
	s_waitcnt vmcnt(3)
	v_pk_add_f32 v[160:161], v[160:161], v[114:115] op_sel_hi:[1,0] neg_lo:[0,1] neg_hi:[0,1]
	v_pk_add_f32 v[162:163], v[162:163], v[114:115] op_sel_hi:[1,0] neg_lo:[0,1] neg_hi:[0,1]
	v_pk_mul_f32 v[160:161], v[160:161], v[114:115] op_sel:[0,1]
	v_pk_mul_f32 v[162:163], v[162:163], v[114:115] op_sel:[0,1]
	v_pk_fma_f32 v[160:161], v[160:161], v[128:129], v[152:153]
	v_pk_fma_f32 v[162:163], v[162:163], v[130:131], v[154:155]
	v_pk_fma_f32 v[148:149], v[160:161], s[14:15], v[148:149] op_sel_hi:[1,0,1]
	v_pk_fma_f32 v[150:151], v[162:163], s[14:15], v[150:151] op_sel_hi:[1,0,1]
	global_store_dwordx4 v110, v[148:151], s[58:59] offset:144
	s_waitcnt vmcnt(3)
	v_pk_add_f32 v[222:223], v[222:223], v[122:123] op_sel_hi:[1,0] neg_lo:[0,1] neg_hi:[0,1]
	v_pk_add_f32 v[224:225], v[224:225], v[122:123] op_sel_hi:[1,0] neg_lo:[0,1] neg_hi:[0,1]
	v_pk_mul_f32 v[222:223], v[222:223], v[122:123] op_sel:[0,1]
	v_pk_mul_f32 v[224:225], v[224:225], v[122:123] op_sel:[0,1]
	v_pk_fma_f32 v[222:223], v[222:223], v[128:129], v[152:153]
	v_pk_fma_f32 v[224:225], v[224:225], v[130:131], v[154:155]
	v_pk_fma_f32 v[98:99], v[222:223], s[14:15], v[98:99] op_sel_hi:[1,0,1]
	v_pk_fma_f32 v[100:101], v[224:225], s[14:15], v[100:101] op_sel_hi:[1,0,1]
	global_store_dwordx4 v111, v[98:101], s[58:59] offset:144
	s_waitcnt vmcnt(3)
	v_pk_add_f32 v[226:227], v[226:227], v[124:125] op_sel_hi:[1,0] neg_lo:[0,1] neg_hi:[0,1]
	v_pk_add_f32 v[228:229], v[228:229], v[124:125] op_sel_hi:[1,0] neg_lo:[0,1] neg_hi:[0,1]
	v_pk_mul_f32 v[226:227], v[226:227], v[124:125] op_sel:[0,1]
	v_pk_mul_f32 v[228:229], v[228:229], v[124:125] op_sel:[0,1]
	v_pk_fma_f32 v[226:227], v[226:227], v[128:129], v[152:153]
	v_pk_fma_f32 v[228:229], v[228:229], v[130:131], v[154:155]
	v_pk_fma_f32 v[82:83], v[226:227], s[14:15], v[82:83] op_sel_hi:[1,0,1]
	v_pk_fma_f32 v[84:85], v[228:229], s[14:15], v[84:85] op_sel_hi:[1,0,1]
	global_store_dwordx4 v112, v[82:85], s[58:59] offset:144
	s_waitcnt vmcnt(3)
	v_pk_add_f32 v[230:231], v[230:231], v[126:127] op_sel_hi:[1,0] neg_lo:[0,1] neg_hi:[0,1]
	v_pk_add_f32 v[232:233], v[232:233], v[126:127] op_sel_hi:[1,0] neg_lo:[0,1] neg_hi:[0,1]
	v_pk_mul_f32 v[230:231], v[230:231], v[126:127] op_sel:[0,1]
	v_pk_mul_f32 v[232:233], v[232:233], v[126:127] op_sel:[0,1]
	v_pk_fma_f32 v[230:231], v[230:231], v[128:129], v[152:153]
	v_pk_fma_f32 v[232:233], v[232:233], v[130:131], v[154:155]
	v_pk_fma_f32 v[70:71], v[230:231], s[14:15], v[70:71] op_sel_hi:[1,0,1]
	v_pk_fma_f32 v[72:73], v[232:233], s[14:15], v[72:73] op_sel_hi:[1,0,1]
	global_store_dwordx4 v113, v[70:73], s[58:59] offset:144
	s_cmp_lg_u32 s101, 0
	s_cbranch_scc1 .LBB0_126
	v_mov_b32_e32 v0, v169
	v_mov_b32_e32 v67, v169
	s_movk_i32 s4, 0xb00
	v_lshrrev_b32_e32 v66, 3, v0
	v_lshrrev_b32_e32 v69, 3, v67
	v_add_u32_e32 v66, s9, v66
	v_add_u32_e32 v69, s10, v69
	v_lshlrev_b32_e32 v0, 3, v0
	v_mul_lo_u32 v66, v66, s4
	v_lshlrev_b32_e32 v67, 3, v67
	v_mul_lo_u32 v69, v69, s4
	v_and_or_b32 v0, v0, 56, v66
	v_and_or_b32 v72, v67, 56, v69
	v_add_u32_e32 v66, 0x16000, v0
	v_add_u32_e32 v68, 0x2c000, v0
	v_add_u32_e32 v70, 0x42000, v0
	v_add_u32_e32 v74, 0x16000, v72
	v_add_u32_e32 v76, 0x2c000, v72
	v_add_u32_e32 v78, 0x42000, v72
	s_mov_b64 s[42:43], 0
	s_branch .LBB0_126

.LBB0_157:
	s_setprio 1
	s_add_u32 s98, s38, s36
	s_addc_u32 s99, s39, 0
	s_add_u32 s98, s98, 0x80
	s_addc_u32 s99, s99, 0
	v_add_u32_e32 v122, v119, v118
	v_add_u32_e32 v124, v119, v120
	v_add_u32_e32 v123, v121, v120
	ds_read_b128 v[126:129], v122 offset:16384
	ds_read_b128 v[130:133], v124
	ds_read_b128 v[144:147], v122 offset:18432
	ds_read_b128 v[158:161], v122 offset:20480
	ds_read_b128 v[162:165], v122 offset:22528
	ds_read_b128 v[134:137], v124 offset:2048
	ds_read_b128 v[140:143], v124 offset:4096
	ds_read_b128 v[148:151], v124 offset:6144
	s_add_u32 m0, s100, 0x8000
	s_waitcnt lgkmcnt(6)
	v_mfma_f32_16x16x32_bf16 v[34:37], v[126:129], v[130:133], v[34:37]
	global_load_lds_dwordx4 v194, s[98:99]
	s_waitcnt lgkmcnt(5)
	v_mfma_f32_16x16x32_bf16 v[94:97], v[144:147], v[130:133], v[94:97]
	ds_read_b128 v[198:201], v123
	s_add_u32 m0, s100, 0xc000
	s_waitcnt lgkmcnt(5)
	v_mfma_f32_16x16x32_bf16 v[38:41], v[158:161], v[130:133], v[38:41]
	global_load_lds_dwordx4 v195, s[98:99]
	s_waitcnt lgkmcnt(4)
	v_mfma_f32_16x16x32_bf16 v[90:93], v[162:165], v[130:133], v[90:93]
	ds_read_b128 v[206:209], v123 offset:2048
	s_add_u32 m0, s100, 0x9000
	s_waitcnt lgkmcnt(4)
	v_mfma_f32_16x16x32_bf16 v[42:45], v[126:129], v[134:137], v[42:45]
	global_load_lds_dwordx4 v196, s[98:99]
	v_mfma_f32_16x16x32_bf16 v[86:89], v[144:147], v[134:137], v[86:89]
	ds_read_b128 v[214:217], v123 offset:4096
	s_add_u32 m0, s100, 0xd000
	v_mfma_f32_16x16x32_bf16 v[46:49], v[158:161], v[134:137], v[46:49]
	global_load_lds_dwordx4 v197, s[98:99]
	v_mfma_f32_16x16x32_bf16 v[82:85], v[162:165], v[134:137], v[82:85]
	v_add_u32_e32 v130, v121, v118
	ds_read_b128 v[132:135], v123 offset:6144
	s_add_u32 m0, s100, 0xa000
	s_waitcnt lgkmcnt(5)
	v_mfma_f32_16x16x32_bf16 v[50:53], v[126:129], v[140:143], v[50:53]
	global_load_lds_dwordx4 v202, s[98:99]
	v_mfma_f32_16x16x32_bf16 v[78:81], v[144:147], v[140:143], v[78:81]
	ds_read_b128 v[226:229], v130 offset:16384
	s_add_u32 m0, s100, 0xe000
	v_mfma_f32_16x16x32_bf16 v[54:57], v[158:161], v[140:143], v[54:57]
	global_load_lds_dwordx4 v203, s[98:99]
	v_mfma_f32_16x16x32_bf16 v[70:73], v[162:165], v[140:143], v[70:73]
	ds_read_b128 v[140:143], v130 offset:18432
	s_add_u32 m0, s100, 0xb000
	s_waitcnt lgkmcnt(6)
	v_mfma_f32_16x16x32_bf16 v[58:61], v[126:129], v[148:151], v[58:61]
	global_load_lds_dwordx4 v204, s[98:99]
	v_mfma_f32_16x16x32_bf16 v[66:69], v[144:147], v[148:151], v[66:69]
	ds_read_b128 v[144:147], v130 offset:20480
	s_add_u32 m0, s100, 0xf000
	v_mfma_f32_16x16x32_bf16 v[62:65], v[158:161], v[148:151], v[62:65]
	global_load_lds_dwordx4 v205, s[98:99]
	v_mfma_f32_16x16x32_bf16 v[74:77], v[162:165], v[148:151], v[74:77]
	ds_read_b128 v[148:151], v130 offset:22528
	s_waitcnt lgkmcnt(3)
	v_mfma_f32_16x16x32_bf16 v[34:37], v[226:229], v[198:201], v[34:37]
	s_waitcnt lgkmcnt(2)
	v_mfma_f32_16x16x32_bf16 v[94:97], v[140:143], v[198:201], v[94:97]
	s_waitcnt lgkmcnt(1)
	v_mfma_f32_16x16x32_bf16 v[38:41], v[144:147], v[198:201], v[38:41]
	s_waitcnt lgkmcnt(0)
	v_mfma_f32_16x16x32_bf16 v[90:93], v[148:151], v[198:201], v[90:93]
	v_mfma_f32_16x16x32_bf16 v[42:45], v[226:229], v[206:209], v[42:45]
	v_mfma_f32_16x16x32_bf16 v[86:89], v[140:143], v[206:209], v[86:89]
	v_mfma_f32_16x16x32_bf16 v[46:49], v[144:147], v[206:209], v[46:49]
	v_mfma_f32_16x16x32_bf16 v[82:85], v[148:151], v[206:209], v[82:85]
	v_mfma_f32_16x16x32_bf16 v[50:53], v[226:229], v[214:217], v[50:53]
	v_mfma_f32_16x16x32_bf16 v[78:81], v[140:143], v[214:217], v[78:81]
	v_mfma_f32_16x16x32_bf16 v[54:57], v[144:147], v[214:217], v[54:57]
	v_mfma_f32_16x16x32_bf16 v[70:73], v[148:151], v[214:217], v[70:73]
	v_mfma_f32_16x16x32_bf16 v[58:61], v[226:229], v[132:135], v[58:61]
	v_mfma_f32_16x16x32_bf16 v[66:69], v[140:143], v[132:135], v[66:69]
	v_mfma_f32_16x16x32_bf16 v[62:65], v[144:147], v[132:135], v[62:65]
	v_mfma_f32_16x16x32_bf16 v[74:77], v[148:151], v[132:135], v[74:77]
	s_waitcnt vmcnt(0)
	s_setprio 0
	s_waitcnt lgkmcnt(0)
	s_barrier
	s_setprio 1
	s_add_u32 s98, s98, 0x80
	s_addc_u32 s99, s99, 0
	ds_read_b128 v[26:29], v122 offset:49152
	ds_read_b128 v[10:13], v124 offset:32768
	ds_read_b128 v[30:33], v122 offset:51200
	ds_read_b128 v[144:147], v122 offset:53248
	ds_read_b128 v[148:151], v122 offset:55296
	ds_read_b128 v[18:21], v124 offset:34816
	ds_read_b128 v[132:135], v124 offset:36864
	ds_read_b128 v[140:143], v124 offset:38912
	s_add_u32 m0, s100, 0x0
	s_waitcnt lgkmcnt(6)
	v_mfma_f32_16x16x32_bf16 v[34:37], v[26:29], v[10:13], v[34:37]
	global_load_lds_dwordx4 v194, s[98:99]
	s_waitcnt lgkmcnt(5)
	v_mfma_f32_16x16x32_bf16 v[94:97], v[30:33], v[10:13], v[94:97]
	ds_read_b128 v[162:165], v123 offset:32768
	s_add_u32 m0, s100, 0x4000
	s_waitcnt lgkmcnt(5)
	v_mfma_f32_16x16x32_bf16 v[38:41], v[144:147], v[10:13], v[38:41]
	global_load_lds_dwordx4 v195, s[98:99]
	s_waitcnt lgkmcnt(4)
	v_mfma_f32_16x16x32_bf16 v[90:93], v[148:151], v[10:13], v[90:93]
	ds_read_b128 v[198:201], v123 offset:34816
	s_add_u32 m0, s100, 0x1000
	s_waitcnt lgkmcnt(4)
	v_mfma_f32_16x16x32_bf16 v[42:45], v[26:29], v[18:21], v[42:45]
	global_load_lds_dwordx4 v196, s[98:99]
	v_mfma_f32_16x16x32_bf16 v[86:89], v[30:33], v[18:21], v[86:89]
	ds_read_b128 v[206:209], v123 offset:36864
	s_add_u32 m0, s100, 0x5000
	v_mfma_f32_16x16x32_bf16 v[46:49], v[144:147], v[18:21], v[46:49]
	global_load_lds_dwordx4 v197, s[98:99]
	v_mfma_f32_16x16x32_bf16 v[82:85], v[148:151], v[18:21], v[82:85]
	ds_read_b128 v[214:217], v123 offset:38912
	s_add_u32 m0, s100, 0x2000
	s_waitcnt lgkmcnt(5)
	v_mfma_f32_16x16x32_bf16 v[50:53], v[26:29], v[132:135], v[50:53]
	global_load_lds_dwordx4 v202, s[98:99]
	v_mfma_f32_16x16x32_bf16 v[78:81], v[30:33], v[132:135], v[78:81]
	ds_read_b128 v[226:229], v130 offset:49152
	s_add_u32 m0, s100, 0x6000
	v_mfma_f32_16x16x32_bf16 v[54:57], v[144:147], v[132:135], v[54:57]
	global_load_lds_dwordx4 v203, s[98:99]
	v_mfma_f32_16x16x32_bf16 v[70:73], v[148:151], v[132:135], v[70:73]
	ds_read_b128 v[132:135], v130 offset:51200
	s_add_u32 m0, s100, 0x3000
	s_waitcnt lgkmcnt(6)
	v_mfma_f32_16x16x32_bf16 v[58:61], v[26:29], v[140:143], v[58:61]
	global_load_lds_dwordx4 v204, s[98:99]
	v_mfma_f32_16x16x32_bf16 v[66:69], v[30:33], v[140:143], v[66:69]
	ds_read_b128 v[234:237], v130 offset:53248
	s_add_u32 m0, s100, 0x7000
	v_mfma_f32_16x16x32_bf16 v[62:65], v[144:147], v[140:143], v[62:65]
	global_load_lds_dwordx4 v205, s[98:99]
	v_mfma_f32_16x16x32_bf16 v[74:77], v[148:151], v[140:143], v[74:77]
	ds_read_b128 v[140:143], v130 offset:55296
	s_waitcnt lgkmcnt(3)
	v_mfma_f32_16x16x32_bf16 v[34:37], v[226:229], v[162:165], v[34:37]
	s_waitcnt lgkmcnt(2)
	v_mfma_f32_16x16x32_bf16 v[94:97], v[132:135], v[162:165], v[94:97]
	s_waitcnt lgkmcnt(1)
	v_mfma_f32_16x16x32_bf16 v[38:41], v[234:237], v[162:165], v[38:41]
	s_waitcnt lgkmcnt(0)
	v_mfma_f32_16x16x32_bf16 v[90:93], v[140:143], v[162:165], v[90:93]
	v_mfma_f32_16x16x32_bf16 v[42:45], v[226:229], v[198:201], v[42:45]
	v_mfma_f32_16x16x32_bf16 v[86:89], v[132:135], v[198:201], v[86:89]
	v_mfma_f32_16x16x32_bf16 v[46:49], v[234:237], v[198:201], v[46:49]
	v_mfma_f32_16x16x32_bf16 v[82:85], v[140:143], v[198:201], v[82:85]
	v_mfma_f32_16x16x32_bf16 v[50:53], v[226:229], v[206:209], v[50:53]
	v_mfma_f32_16x16x32_bf16 v[78:81], v[132:135], v[206:209], v[78:81]
	v_mfma_f32_16x16x32_bf16 v[54:57], v[234:237], v[206:209], v[54:57]
	v_mfma_f32_16x16x32_bf16 v[70:73], v[140:143], v[206:209], v[70:73]
	v_mfma_f32_16x16x32_bf16 v[58:61], v[226:229], v[214:217], v[58:61]
	v_mfma_f32_16x16x32_bf16 v[66:69], v[132:135], v[214:217], v[66:69]
	v_mfma_f32_16x16x32_bf16 v[62:65], v[234:237], v[214:217], v[62:65]
	v_mfma_f32_16x16x32_bf16 v[74:77], v[140:143], v[214:217], v[74:77]
	s_waitcnt vmcnt(0)
	s_setprio 0
	s_add_i32 s5, s5, 2
	s_add_u32 s38, s38, 0x100
	s_addc_u32 s39, s39, 0
	s_cmp_lt_u32 s5, 12
	s_waitcnt lgkmcnt(0)
	s_barrier
	s_cbranch_scc1 .LBB0_157
	v_mov_b32_e32 v2, v194
	v_mov_b32_e32 v3, v195
	v_mov_b32_e32 v4, v196
	v_mov_b32_e32 v5, v197
	v_mov_b32_e32 v6, v202
	v_mov_b32_e32 v7, v203
	v_mov_b32_e32 v8, v204
	v_mov_b32_e32 v9, v205
	s_add_u32 s98, s38, s36
	s_addc_u32 s99, s39, 0
	s_add_u32 s98, s98, 0x80
	s_addc_u32 s99, s99, 0
	s_add_i32 s5, s11, s2
	s_cmpk_lt_u32 s5, 0x100
	s_cselect_b64 s[44:45], -1, 0
	s_and_b64 s[8:9], s[44:45], exec
	s_cselect_b32 s9, s5, s11
	s_lshr_b32 s8, s9, 3
	s_and_b32 s8, s8, 0x1fffff8
	s_add_i32 s8, s8, s21
	s_and_b32 s11, s9, 7
	v_mov_b32_e32 v0, v169
	s_or_b32 s8, s8, s11
	s_lshl_b32 s8, s8, 7
	v_lshrrev_b32_e32 v98, 3, v0
	v_lshlrev_b32_e32 v0, 3, v0
	v_add_u32_e32 v98, s8, v98
	v_and_b32_e32 v0, 56, v0
	v_lshl_or_b32 v0, v98, 10, v0
	v_mov_b32_e32 v98, v169
	s_lshl_b32 s9, s9, 4
	s_and_b32 s9, s9, 0x380
	v_lshrrev_b32_e32 v99, 3, v98
	v_lshlrev_b32_e32 v98, 3, v98
	v_add_u32_e32 v99, s9, v99
	v_and_b32_e32 v98, 56, v98
	v_add_u32_e32 v114, 0x8000, v0
	v_add_u32_e32 v136, 0x10000, v0
	v_lshl_or_b32 v162, v99, 10, v98
	v_add_u32_e32 v166, 0x18000, v0
	v_add_u32_e32 v174, 0x8000, v162
	v_add_u32_e32 v176, 0x10000, v162
	v_add_u32_e32 v178, 0x18000, v162
	s_setprio 1
	ds_read_b128 v[98:101], v122 offset:16384
	ds_read_b128 v[102:105], v124
	ds_read_b128 v[110:113], v122 offset:18432
	ds_read_b128 v[132:135], v122 offset:20480
	ds_read_b128 v[140:143], v122 offset:22528
	ds_read_b128 v[106:109], v124 offset:2048
	ds_read_b128 v[118:121], v124 offset:4096
	ds_read_b128 v[126:129], v124 offset:6144
	v_lshrrev_b32_e32 v14, 3, v169
	v_and_b32_e32 v15, 3, v14
	v_bfe_u32 v16, v14, 4, 1
	v_lshl_or_b32 v15, v16, 2, v15
	v_bfe_u32 v16, v14, 2, 1
	v_lshl_or_b32 v15, v16, 3, v15
	v_bfe_u32 v16, v14, 3, 1
	v_lshl_or_b32 v15, v16, 4, v15
	v_sub_u32_e32 v15, v15, v14
	v_mul_i32_i24_e32 v15, 0x400, v15
	v_and_b32_e32 v14, 7, v14
	v_lshlrev_b32_e32 v14, 3, v14
	v_xor_b32_e32 v0, v0, v14
	v_add_u32_e32 v162, v162, v15
	v_xor_b32_e32 v162, v162, v14
	v_xor_b32_e32 v114, v114, v14
	v_add_u32_e32 v174, v174, v15
	v_xor_b32_e32 v174, v174, v14
	v_xor_b32_e32 v136, v136, v14
	v_add_u32_e32 v176, v176, v15
	v_xor_b32_e32 v176, v176, v14
	v_xor_b32_e32 v166, v166, v14
	v_add_u32_e32 v178, v178, v15
	v_xor_b32_e32 v178, v178, v14
	v_readlane_b32 s14, v254, 45
	v_readlane_b32 s15, v254, 46
	v_mov_b32_e32 v163, v1
	v_mov_b32_e32 v115, v1
	v_mov_b32_e32 v175, v1
	v_mov_b32_e32 v137, v1
	v_mov_b32_e32 v177, v1
	v_mov_b32_e32 v167, v1
	v_mov_b32_e32 v179, v1
	v_lshl_add_u64 v[180:181], v[0:1], 1, s[14:15]
	v_lshl_add_u64 v[186:187], v[162:163], 1, s[34:35]
	v_lshl_add_u64 v[188:189], v[114:115], 1, s[14:15]
	v_lshl_add_u64 v[174:175], v[174:175], 1, s[34:35]
	v_lshl_add_u64 v[136:137], v[136:137], 1, s[14:15]
	v_lshl_add_u64 v[176:177], v[176:177], 1, s[34:35]
	v_lshl_add_u64 v[166:167], v[166:167], 1, s[14:15]
	v_lshl_add_u64 v[178:179], v[178:179], 1, s[34:35]
	s_add_u32 m0, s100, 0x8000
	s_waitcnt lgkmcnt(6)
	v_mfma_f32_16x16x32_bf16 v[144:147], v[98:101], v[102:105], v[34:37]
	global_load_lds_dwordx4 v2, s[98:99]
	s_waitcnt lgkmcnt(5)
	v_mfma_f32_16x16x32_bf16 v[94:97], v[110:113], v[102:105], v[94:97]
	ds_read_b128 v[148:151], v123
	s_add_u32 m0, s100, 0xc000
	s_waitcnt lgkmcnt(5)
	v_mfma_f32_16x16x32_bf16 v[158:161], v[132:135], v[102:105], v[38:41]
	global_load_lds_dwordx4 v3, s[98:99]
	s_waitcnt lgkmcnt(4)
	v_mfma_f32_16x16x32_bf16 v[90:93], v[140:143], v[102:105], v[90:93]
	ds_read_b128 v[102:105], v123 offset:2048
	s_add_u32 m0, s100, 0x9000
	s_waitcnt lgkmcnt(4)
	v_mfma_f32_16x16x32_bf16 v[162:165], v[98:101], v[106:109], v[42:45]
	global_load_lds_dwordx4 v4, s[98:99]
	v_mfma_f32_16x16x32_bf16 v[86:89], v[110:113], v[106:109], v[86:89]
	ds_read_b128 v[194:197], v123 offset:4096
	s_add_u32 m0, s100, 0xd000
	v_mfma_f32_16x16x32_bf16 v[198:201], v[132:135], v[106:109], v[46:49]
	global_load_lds_dwordx4 v5, s[98:99]
	v_mfma_f32_16x16x32_bf16 v[82:85], v[140:143], v[106:109], v[82:85]
	ds_read_b128 v[106:109], v123 offset:6144
	s_add_u32 m0, s100, 0xa000
	s_waitcnt lgkmcnt(5)
	v_mfma_f32_16x16x32_bf16 v[202:205], v[98:101], v[118:121], v[50:53]
	global_load_lds_dwordx4 v6, s[98:99]
	v_mfma_f32_16x16x32_bf16 v[78:81], v[110:113], v[118:121], v[78:81]
	ds_read_b128 v[206:209], v130 offset:16384
	s_add_u32 m0, s100, 0xe000
	v_mfma_f32_16x16x32_bf16 v[210:213], v[132:135], v[118:121], v[54:57]
	global_load_lds_dwordx4 v7, s[98:99]
	v_mfma_f32_16x16x32_bf16 v[70:73], v[140:143], v[118:121], v[70:73]
	ds_read_b128 v[118:121], v130 offset:18432
	s_add_u32 m0, s100, 0xb000
	s_waitcnt lgkmcnt(6)
	v_mfma_f32_16x16x32_bf16 v[98:101], v[98:101], v[126:129], v[58:61]
	global_load_lds_dwordx4 v8, s[98:99]
	v_mfma_f32_16x16x32_bf16 v[66:69], v[110:113], v[126:129], v[66:69]
	ds_read_b128 v[110:113], v130 offset:20480
	s_add_u32 m0, s100, 0xf000
	v_mfma_f32_16x16x32_bf16 v[132:135], v[132:135], v[126:129], v[62:65]
	global_load_lds_dwordx4 v9, s[98:99]
	v_mfma_f32_16x16x32_bf16 v[74:77], v[140:143], v[126:129], v[74:77]
	ds_read_b128 v[126:129], v130 offset:22528
	s_waitcnt lgkmcnt(3)
	v_mfma_f32_16x16x32_bf16 v[140:143], v[206:209], v[148:151], v[144:147]
	s_waitcnt lgkmcnt(2)
	v_mfma_f32_16x16x32_bf16 v[94:97], v[118:121], v[148:151], v[94:97]
	s_waitcnt lgkmcnt(1)
	v_mfma_f32_16x16x32_bf16 v[144:147], v[110:113], v[148:151], v[158:161]
	s_waitcnt lgkmcnt(0)
	v_mfma_f32_16x16x32_bf16 v[90:93], v[126:129], v[148:151], v[90:93]
	v_mfma_f32_16x16x32_bf16 v[148:151], v[206:209], v[102:105], v[162:165]
	v_mfma_f32_16x16x32_bf16 v[86:89], v[118:121], v[102:105], v[86:89]
	v_mfma_f32_16x16x32_bf16 v[158:161], v[110:113], v[102:105], v[198:201]
	v_mfma_f32_16x16x32_bf16 v[82:85], v[126:129], v[102:105], v[82:85]
	v_mfma_f32_16x16x32_bf16 v[102:105], v[206:209], v[194:197], v[202:205]
	v_mfma_f32_16x16x32_bf16 v[78:81], v[118:121], v[194:197], v[78:81]
	v_mfma_f32_16x16x32_bf16 v[162:165], v[110:113], v[194:197], v[210:213]
	v_mfma_f32_16x16x32_bf16 v[70:73], v[126:129], v[194:197], v[70:73]
	v_mfma_f32_16x16x32_bf16 v[98:101], v[206:209], v[106:109], v[98:101]
	v_mfma_f32_16x16x32_bf16 v[66:69], v[118:121], v[106:109], v[66:69]
	v_mfma_f32_16x16x32_bf16 v[110:113], v[110:113], v[106:109], v[132:135]
	v_mfma_f32_16x16x32_bf16 v[74:77], v[126:129], v[106:109], v[74:77]
	s_waitcnt vmcnt(0)
	s_setprio 0
	s_waitcnt lgkmcnt(0)
	s_barrier
	s_setprio 1
	ds_read_b128 v[26:29], v122 offset:49152
	ds_read_b128 v[10:13], v124 offset:32768
	ds_read_b128 v[18:21], v124 offset:34816
	ds_read_b128 v[30:33], v122 offset:51200
	ds_read_b128 v[106:109], v124 offset:36864
	ds_read_b128 v[114:117], v124 offset:38912
	ds_read_b128 v[118:121], v122 offset:53248
	ds_read_b128 v[124:127], v122 offset:55296
	s_add_u32 m0, s100, 0x0
	s_waitcnt lgkmcnt(6)
	v_mfma_f32_16x16x32_bf16 v[132:135], v[26:29], v[10:13], v[140:143]
	global_load_lds_dwordx4 v[180:181], off
	s_waitcnt lgkmcnt(4)
	v_mfma_f32_16x16x32_bf16 v[94:97], v[30:33], v[10:13], v[94:97]
	ds_read_b128 v[140:143], v123 offset:32768
	s_add_u32 m0, s100, 0x4000
	s_waitcnt lgkmcnt(2)
	v_mfma_f32_16x16x32_bf16 v[144:147], v[118:121], v[10:13], v[144:147]
	global_load_lds_dwordx4 v[186:187], off
	s_waitcnt lgkmcnt(1)
	v_mfma_f32_16x16x32_bf16 v[90:93], v[124:127], v[10:13], v[90:93]
	ds_read_b128 v[194:197], v123 offset:34816
	s_add_u32 m0, s100, 0x1000
	v_mfma_f32_16x16x32_bf16 v[148:151], v[26:29], v[18:21], v[148:151]
	global_load_lds_dwordx4 v[188:189], off
	v_mfma_f32_16x16x32_bf16 v[86:89], v[30:33], v[18:21], v[86:89]
	ds_read_b128 v[198:201], v123 offset:36864
	s_add_u32 m0, s100, 0x5000
	v_mfma_f32_16x16x32_bf16 v[158:161], v[118:121], v[18:21], v[158:161]
	global_load_lds_dwordx4 v[174:175], off
	v_mfma_f32_16x16x32_bf16 v[82:85], v[124:127], v[18:21], v[82:85]
	ds_read_b128 v[202:205], v123 offset:38912
	s_add_u32 m0, s100, 0x2000
	v_mfma_f32_16x16x32_bf16 v[206:209], v[26:29], v[106:109], v[102:105]
	global_load_lds_dwordx4 v[136:137], off
	v_mfma_f32_16x16x32_bf16 v[78:81], v[30:33], v[106:109], v[78:81]
	ds_read_b128 v[210:213], v130 offset:49152
	s_add_u32 m0, s100, 0x6000
	v_mfma_f32_16x16x32_bf16 v[162:165], v[118:121], v[106:109], v[162:165]
	global_load_lds_dwordx4 v[176:177], off
	v_mfma_f32_16x16x32_bf16 v[70:73], v[124:127], v[106:109], v[70:73]
	ds_read_b128 v[214:217], v130 offset:51200
	s_add_u32 m0, s100, 0x3000
	v_mfma_f32_16x16x32_bf16 v[218:221], v[26:29], v[114:117], v[98:101]
	global_load_lds_dwordx4 v[166:167], off
	v_mfma_f32_16x16x32_bf16 v[66:69], v[30:33], v[114:117], v[66:69]
	ds_read_b128 v[222:225], v130 offset:53248
	s_add_u32 m0, s100, 0x7000
	v_mfma_f32_16x16x32_bf16 v[226:229], v[118:121], v[114:117], v[110:113]
	global_load_lds_dwordx4 v[178:179], off
	v_mfma_f32_16x16x32_bf16 v[230:233], v[124:127], v[114:117], v[74:77]
	s_waitcnt lgkmcnt(2)
	v_mfma_f32_16x16x32_bf16 v[126:129], v[210:213], v[140:143], v[132:135]
	ds_read_b128 v[130:133], v130 offset:55296
	s_waitcnt lgkmcnt(2)
	v_mfma_f32_16x16x32_bf16 v[122:125], v[214:217], v[140:143], v[94:97]
	s_waitcnt lgkmcnt(1)
	v_mfma_f32_16x16x32_bf16 v[118:121], v[222:225], v[140:143], v[144:147]
	s_waitcnt lgkmcnt(0)
	v_mfma_f32_16x16x32_bf16 v[114:117], v[130:133], v[140:143], v[90:93]
	v_mfma_f32_16x16x32_bf16 v[110:113], v[210:213], v[194:197], v[148:151]
	v_mfma_f32_16x16x32_bf16 v[106:109], v[214:217], v[194:197], v[86:89]
	v_mfma_f32_16x16x32_bf16 v[102:105], v[222:225], v[194:197], v[158:161]
	v_mfma_f32_16x16x32_bf16 v[98:101], v[130:133], v[194:197], v[82:85]
	v_mfma_f32_16x16x32_bf16 v[94:97], v[210:213], v[198:201], v[206:209]
	v_mfma_f32_16x16x32_bf16 v[90:93], v[214:217], v[198:201], v[78:81]
	v_mfma_f32_16x16x32_bf16 v[86:89], v[222:225], v[198:201], v[162:165]
	v_mfma_f32_16x16x32_bf16 v[82:85], v[130:133], v[198:201], v[70:73]
	v_mfma_f32_16x16x32_bf16 v[78:81], v[210:213], v[202:205], v[218:221]
	v_mfma_f32_16x16x32_bf16 v[74:77], v[214:217], v[202:205], v[66:69]
	v_mfma_f32_16x16x32_bf16 v[70:73], v[222:225], v[202:205], v[226:229]
	v_mfma_f32_16x16x32_bf16 v[66:69], v[130:133], v[202:205], v[230:233]
	s_setprio 0
	v_add_u32_e32 v134, s4, v152
	v_ashrrev_i32_e32 v135, 31, v134
	v_lshlrev_b64 v[136:137], 12, v[134:135]
	v_or_b32_e32 v140, s10, v153
	v_mov_b32_e32 v141, v1
	v_cndmask_b32_e64 v0, 0, 1, s[42:43]
	v_lshl_add_u64 v[130:131], s[40:41], 0, v[136:137]
	v_cmp_ne_u32_e64 s[38:39], 1, v0
	s_andn2_b64 vcc, exec, s[42:43]
	v_lshl_add_u64 v[146:147], v[140:141], 2, v[130:131]
	s_barrier
	v_readlane_b32 s48, v253, 18
	v_readlane_b32 s49, v253, 19
	v_readlane_b32 s50, v253, 20
	v_readlane_b32 s51, v253, 21
	v_readlane_b32 s52, v253, 22
	v_readlane_b32 s53, v253, 23
	v_readlane_b32 s54, v253, 24
	v_readlane_b32 s55, v253, 25
	v_readlane_b32 s56, v253, 26
	v_readlane_b32 s57, v253, 27
	v_readlane_b32 s58, v253, 28
	v_readlane_b32 s59, v253, 29
	v_readlane_b32 s60, v253, 30
	v_readlane_b32 s61, v253, 31
	v_readlane_b32 s62, v253, 32
	v_readlane_b32 s63, v253, 33
	v_or_b32_e32 v0, s10, v153
	v_lshlrev_b32_e32 v0, 2, v0
	v_add_u32_e32 v130, s4, v152
	v_lshlrev_b32_e32 v158, 3, v130
	v_lshlrev_b32_e32 v130, 12, v130
	v_add_u32_e32 v130, v130, v0
	v_add_u32_e32 v131, s4, v154
	v_lshlrev_b32_e32 v162, 3, v131
	v_lshlrev_b32_e32 v131, 12, v131
	v_add_u32_e32 v131, v131, v0
	v_add_u32_e32 v132, s4, v155
	v_lshlrev_b32_e32 v234, 3, v132
	v_lshlrev_b32_e32 v132, 12, v132
	v_add_u32_e32 v132, v132, v0
	v_add_u32_e32 v133, s4, v156
	v_lshlrev_b32_e32 v238, 3, v133
	v_lshlrev_b32_e32 v133, 12, v133
	v_add_u32_e32 v133, v133, v0
	s_mov_b32 s10, 0x3fb504f3
	s_cmp_lg_u64 s[40:41], 0
	s_cbranch_scc0 .Lepi_ln_157
	global_load_dwordx4 v[158:161], v130, s[40:41]
	global_load_dwordx4 v[162:165], v131, s[40:41]
	global_load_dwordx4 v[234:237], v132, s[40:41]
	global_load_dwordx4 v[238:241], v133, s[40:41]
	s_waitcnt vmcnt(3)
	v_pk_fma_f32 v[126:127], v[158:159], s[10:11], v[126:127] op_sel_hi:[1,0,1]
	v_pk_fma_f32 v[128:129], v[160:161], s[10:11], v[128:129] op_sel_hi:[1,0,1]
	global_store_dwordx4 v130, v[126:129], s[62:63]
	s_waitcnt vmcnt(3)
	v_pk_fma_f32 v[110:111], v[162:163], s[10:11], v[110:111] op_sel_hi:[1,0,1]
	v_pk_fma_f32 v[112:113], v[164:165], s[10:11], v[112:113] op_sel_hi:[1,0,1]
	global_store_dwordx4 v131, v[110:113], s[62:63]
	s_waitcnt vmcnt(3)
	v_pk_fma_f32 v[94:95], v[234:235], s[10:11], v[94:95] op_sel_hi:[1,0,1]
	v_pk_fma_f32 v[96:97], v[236:237], s[10:11], v[96:97] op_sel_hi:[1,0,1]
	global_store_dwordx4 v132, v[94:97], s[62:63]
	s_waitcnt vmcnt(3)
	v_pk_fma_f32 v[78:79], v[238:239], s[10:11], v[78:79] op_sel_hi:[1,0,1]
	v_pk_fma_f32 v[80:81], v[240:241], s[10:11], v[80:81] op_sel_hi:[1,0,1]
	global_store_dwordx4 v133, v[78:81], s[62:63]
	global_load_dwordx4 v[158:161], v130, s[40:41] offset:16
	global_load_dwordx4 v[162:165], v131, s[40:41] offset:16
	global_load_dwordx4 v[234:237], v132, s[40:41] offset:16
	global_load_dwordx4 v[238:241], v133, s[40:41] offset:16
	s_waitcnt vmcnt(3)
	v_pk_fma_f32 v[122:123], v[158:159], s[10:11], v[122:123] op_sel_hi:[1,0,1]
	v_pk_fma_f32 v[124:125], v[160:161], s[10:11], v[124:125] op_sel_hi:[1,0,1]
	global_store_dwordx4 v130, v[122:125], s[62:63] offset:16
	s_waitcnt vmcnt(3)
	v_pk_fma_f32 v[106:107], v[162:163], s[10:11], v[106:107] op_sel_hi:[1,0,1]
	v_pk_fma_f32 v[108:109], v[164:165], s[10:11], v[108:109] op_sel_hi:[1,0,1]
	global_store_dwordx4 v131, v[106:109], s[62:63] offset:16
	s_waitcnt vmcnt(3)
	v_pk_fma_f32 v[90:91], v[234:235], s[10:11], v[90:91] op_sel_hi:[1,0,1]
	v_pk_fma_f32 v[92:93], v[236:237], s[10:11], v[92:93] op_sel_hi:[1,0,1]
	global_store_dwordx4 v132, v[90:93], s[62:63] offset:16
	s_waitcnt vmcnt(3)
	v_pk_fma_f32 v[74:75], v[238:239], s[10:11], v[74:75] op_sel_hi:[1,0,1]
	v_pk_fma_f32 v[76:77], v[240:241], s[10:11], v[76:77] op_sel_hi:[1,0,1]
	global_store_dwordx4 v133, v[74:77], s[62:63] offset:16
	global_load_dwordx4 v[158:161], v130, s[40:41] offset:128
	global_load_dwordx4 v[162:165], v131, s[40:41] offset:128
	global_load_dwordx4 v[234:237], v132, s[40:41] offset:128
	global_load_dwordx4 v[238:241], v133, s[40:41] offset:128
	s_waitcnt vmcnt(3)
	v_pk_fma_f32 v[118:119], v[158:159], s[10:11], v[118:119] op_sel_hi:[1,0,1]
	v_pk_fma_f32 v[120:121], v[160:161], s[10:11], v[120:121] op_sel_hi:[1,0,1]
	global_store_dwordx4 v130, v[118:121], s[62:63] offset:128
	s_waitcnt vmcnt(3)
	v_pk_fma_f32 v[102:103], v[162:163], s[10:11], v[102:103] op_sel_hi:[1,0,1]
	v_pk_fma_f32 v[104:105], v[164:165], s[10:11], v[104:105] op_sel_hi:[1,0,1]
	global_store_dwordx4 v131, v[102:105], s[62:63] offset:128
	s_waitcnt vmcnt(3)
	v_pk_fma_f32 v[86:87], v[234:235], s[10:11], v[86:87] op_sel_hi:[1,0,1]
	v_pk_fma_f32 v[88:89], v[236:237], s[10:11], v[88:89] op_sel_hi:[1,0,1]
	global_store_dwordx4 v132, v[86:89], s[62:63] offset:128
	s_waitcnt vmcnt(3)
	v_pk_fma_f32 v[70:71], v[238:239], s[10:11], v[70:71] op_sel_hi:[1,0,1]
	v_pk_fma_f32 v[72:73], v[240:241], s[10:11], v[72:73] op_sel_hi:[1,0,1]
	global_store_dwordx4 v133, v[70:73], s[62:63] offset:128
	global_load_dwordx4 v[158:161], v130, s[40:41] offset:144
	global_load_dwordx4 v[162:165], v131, s[40:41] offset:144
	global_load_dwordx4 v[234:237], v132, s[40:41] offset:144
	global_load_dwordx4 v[238:241], v133, s[40:41] offset:144
	s_waitcnt vmcnt(3)
	v_pk_fma_f32 v[114:115], v[158:159], s[10:11], v[114:115] op_sel_hi:[1,0,1]
	v_pk_fma_f32 v[116:117], v[160:161], s[10:11], v[116:117] op_sel_hi:[1,0,1]
	global_store_dwordx4 v130, v[114:117], s[62:63] offset:144
	s_waitcnt vmcnt(3)
	v_pk_fma_f32 v[98:99], v[162:163], s[10:11], v[98:99] op_sel_hi:[1,0,1]
	v_pk_fma_f32 v[100:101], v[164:165], s[10:11], v[100:101] op_sel_hi:[1,0,1]
	global_store_dwordx4 v131, v[98:101], s[62:63] offset:144
	s_waitcnt vmcnt(3)
	v_pk_fma_f32 v[82:83], v[234:235], s[10:11], v[82:83] op_sel_hi:[1,0,1]
	v_pk_fma_f32 v[84:85], v[236:237], s[10:11], v[84:85] op_sel_hi:[1,0,1]
	global_store_dwordx4 v132, v[82:85], s[62:63] offset:144
	s_waitcnt vmcnt(3)
	v_pk_fma_f32 v[66:67], v[238:239], s[10:11], v[66:67] op_sel_hi:[1,0,1]
	v_pk_fma_f32 v[68:69], v[240:241], s[10:11], v[68:69] op_sel_hi:[1,0,1]
	global_store_dwordx4 v133, v[66:69], s[62:63] offset:144
	s_branch .Lepi_done_157
